# panel barrier acquire at workgroup scope (buffer_inv sc0) when the panel's four workgroups share one XCD
# speedup vs baseline: 1.0079x; 1.0079x over previous
.LBB0_1159:
	s_or_b64 exec, exec, s[4:5]
	v_readlane_b32 vcc_lo, v252, 43
	v_readlane_b32 vcc_hi, v252, 44
	s_and_b64 vcc, exec, vcc
	s_cbranch_vccz .Lpb_inv_agent
	buffer_inv sc0
	s_branch .Lpb_inv_done
.Lpb_inv_agent:
	buffer_inv sc1
.Lpb_inv_done:
	s_waitcnt vmcnt(0)
.LBB0_1160:
	s_or_b64 exec, exec, s[0:1]
	s_barrier
	s_mov_b64 s[0:1], 0
